# v20: gla_scan K tile relocated to free LDS with a 160-byte row stride (conflict-free ds_read_b128 in the state update)
# baseline (speedup 1.0000x reference)
; #define GS_LOADK(S, n) do { const int c_ = GS_CHUNK(n); \
;             const bf16* kb_ = KDT + ((((size_t)(dir * 2 + b) * 4 + h) * 260 + c_) * 256) * 64; \
;             _Pragma("unroll") for (int j = 0; j < 8; ++j) S[j] = *(const v4u*)(kb_ + (size_t)(ht + 256 * j) * 8); \
;             if (ht < 64) S[8] = *(const v4u*)(ET + (((size_t)(dir * 2 + b) * 4 + h) * 260 + c_) * 256 + ht * 4); } while (0)
; __device__ __forceinline__ void ph_gla_scan(const Args& a, LAS unsigned char* lds) {
;     const int tid = threadIdx.x, lane = tid & 63, wave = __builtin_amdgcn_readfirstlane(tid >> 6), l16 = lane & 15, kg = lane >> 4;
;     const bf16* P = (const bf16*)(a.ws + WS_P);
;     const bf16* KDT = (const bf16*)(a.ws + WS_KDT); const bf16* PC = (const bf16*)(a.ws + WS_PC); const bf16* VT = (const bf16*)(a.ws + WS_VT); const float* ET = (const float*)(a.ws + WS_ET);
;     constexpr int QS = 528, RS = 144, L_K = 33792, L_V = 70656, L_P = 79872, L_E = 89088;
;     for (int item = blockIdx.x; item < 128; item += gridDim.x) {
;         const int chain = item >> 3, dvb = item & 7, b = chain >> 3, h = (chain >> 1) & 3, dir = chain & 1, bh = b * 4 + h;
;     ...
;         if (wave >= 4) {
;             const int ht = tid - 256;
;             v4u Qa[12], Qb[12], Ka[9], Kb[9];
;     ...
; #pragma unroll
;             for (int j = 0; j < 12; ++j) { Qa[j] = (v4u){0u, 0u, 0u, 0u}; Qb[j] = (v4u){0u, 0u, 0u, 0u}; }
; #pragma unroll
;             for (int j = 0; j < 9; ++j) { Ka[j] = (v4u){0u, 0u, 0u, 0u}; Kb[j] = (v4u){0u, 0u, 0u, 0u}; }
;             GS_LOADQ(Qa, 0); GS_LOADK(Ka, 0); GS_LOADQ(Qb, 1); GS_LOADK(Kb, 1);
;             GS_WRITEQ(Qa); GS_LOADQ(Qa, 2);
;             __syncthreads();
.LBB0_295:
	s_cmp_lt_i32 s70, 5
	s_cselect_b64 s[2:3], -1, 0
	s_and_b64 s[6:7], s[2:3], s[0:1]
	s_andn2_b64 vcc, exec, s[6:7]
	s_cbranch_vccnz .LBB0_363
	s_cmpk_gt_i32 s95, 0x7f
	v_readfirstlane_b32 s0, v224
	s_cbranch_scc1 .LBB0_363
	s_add_u32 s22, s68, 0x25b00000
	s_addc_u32 s23, s69, 0
	s_add_u32 s24, s68, 0x2dd00000
	s_addc_u32 s25, s69, 0
	s_add_u32 s26, s68, 0x2ee00000
	s_addc_u32 s27, s69, 0
	s_cmpk_lt_u32 s0, 0x100
	v_add_u32_e32 v4, 0xffffff00, v224
	s_cselect_b64 s[8:9], -1, 0
	s_lshr_b32 s0, s0, 2
	v_lshlrev_b32_e32 v8, 2, v4
	v_lshlrev_b32_e32 v186, 4, v224
	v_and_b32_e32 v182, 15, v224
	s_and_b32 s4, s0, 48
	s_add_i32 s5, 0, 0x11400
	s_add_i32 s10, 0, 0x13800
	v_ashrrev_i32_e32 v9, 31, v8
	v_and_b32_e32 v5, 0x70, v186
	v_bfe_u32 v1, v224, 4, 2
	v_or_b32_e32 v0, s4, v182
	s_movk_i32 s0, 0x90
	v_mov_b32_e32 v2, s5
	s_movk_i32 s1, 0x210
	v_lshl_add_u64 v[8:9], v[8:9], 2, s[68:69]
	s_mov_b64 s[2:3], 0x3f200000
	v_add_u32_e32 v195, s5, v5
	v_add_u32_e32 v197, s10, v5
	v_add_u32_e32 v199, 0, v5
	v_ashrrev_i32_e32 v5, 31, v4
	v_mad_u32_u24 v3, v0, s0, v2
	v_lshlrev_b32_e32 v181, 4, v1
	v_mad_u32_u24 v183, v182, s1, 0
	v_lshlrev_b32_e32 v2, 2, v1
	v_mul_i32_i24_e32 v1, 0xfffffe80, v182
	v_lshl_add_u64 v[184:185], v[8:9], 0, s[2:3]
	v_lshlrev_b32_e32 v8, 4, v4
	v_ashrrev_i32_e32 v188, 5, v4
	v_lshlrev_b64 v[204:205], 4, v[4:5]
	v_lshrrev_b32_e32 v4, 3, v4
	v_add3_u32 v191, v183, v1, v181
	v_lshlrev_b32_e32 v1, 3, v224
	v_add_u32_e32 v9, 0x100, v224
	v_add_u32_e32 v10, 0x200, v224
	v_add_u32_e32 v11, 0x300, v224
	v_or_b32_e32 v12, 0x400, v224
	v_add_u32_e32 v13, 0x500, v224
	v_add_u32_e32 v14, 0x600, v224
	v_mul_i32_i24_e32 v225, 0x90, v4
	v_lshrrev_b32_e32 v4, 3, v224
	v_mov_b32_e32 v0, s10
	v_and_b32_e32 v6, 0xf8, v1
	v_and_b32_e32 v1, 0x1f0, v186
	v_lshrrev_b32_e32 v190, 5, v224
	v_lshrrev_b32_e32 v192, 5, v9
	v_lshrrev_b32_e32 v194, 5, v10
	v_lshrrev_b32_e32 v196, 5, v11
	v_lshrrev_b32_e32 v198, 5, v12
	v_lshrrev_b32_e32 v200, 5, v13
	v_lshrrev_b32_e32 v202, 5, v14
	v_lshlrev_b32_e32 v206, 4, v9
	v_lshlrev_b32_e32 v208, 4, v10
	v_lshlrev_b32_e32 v210, 4, v11
	v_lshlrev_b32_e32 v212, 4, v12
	v_lshlrev_b32_e32 v214, 4, v13
	v_mul_u32_u24_e32 v226, 0x90, v4
	v_lshrrev_b32_e32 v4, 3, v9
	v_lshrrev_b32_e32 v9, 3, v10
	v_lshrrev_b32_e32 v10, 3, v11
	v_lshrrev_b32_e32 v11, 3, v12
	v_lshrrev_b32_e32 v12, 3, v13
	v_lshrrev_b32_e32 v13, 3, v14
	v_mad_u32_u24 v7, v182, s0, v0
	v_mov_b32_e32 v0, 0
	s_movk_i32 s0, 0x140
	v_add_u32_e32 v1, 0, v1
	v_mul_i32_i24_e32 v5, 0x210, v188
	v_mul_u32_u24_e32 v15, 0x210, v190
	v_mul_u32_u24_e32 v16, 0x210, v192
	v_mul_u32_u24_e32 v17, 0x210, v194
	v_mul_u32_u24_e32 v18, 0x210, v196
	v_mul_u32_u24_e32 v19, 0x210, v198
	v_mul_u32_u24_e32 v20, 0x210, v200
	v_mul_u32_u24_e32 v21, 0x210, v202
	v_mul_u32_u24_e32 v4, 0x90, v4
	v_mul_u32_u24_e32 v9, 0x90, v9
	v_mul_u32_u24_e32 v10, 0x90, v10
	v_mul_u32_u24_e32 v11, 0x90, v11
	v_mul_u32_u24_e32 v12, 0x90, v12
	v_mul_u32_u24_e32 v13, 0x90, v13
	s_mov_b32 s11, 0
	v_add_u32_e32 v193, 0x8400, v191
	v_lshl_add_u32 v144, v182, 4, v191
	v_add_u32_e32 v144, 0x18000, v144
	v_cmp_gt_u32_e64 s[0:1], s0, v224
	v_ashrrev_i32_e32 v189, 31, v188
	v_mov_b32_e32 v201, v0
	v_mov_b32_e32 v203, v0
	v_mov_b32_e32 v187, v0
	v_mov_b32_e32 v207, v0
	v_mov_b32_e32 v209, v0
	v_mov_b32_e32 v211, v0
	v_mov_b32_e32 v213, v0
	v_mov_b32_e32 v215, v0
	v_lshlrev_b32_e32 v216, 4, v14
	v_mov_b32_e32 v217, v0
	s_mov_b32 s28, 0x5300000
	s_lshl_b32 s29, s4, 1
	v_lshlrev_b32_e32 v218, 1, v2
	v_add_u32_e32 v227, v3, v181
	v_add_u32_e32 v228, v7, v181
	s_mov_b32 s30, 0x10000
	s_mov_b32 s31, 0x20000
	s_mov_b32 s33, 0x30000
	s_movk_i32 s34, 0x103
	v_lshlrev_b32_e32 v220, 1, v6
	s_movk_i32 s35, 0x3000
	v_mov_b32_e32 v229, 0x3000
	v_add_u32_e32 v230, v1, v5
	v_add_u32_e32 v231, v1, v15
	v_add_u32_e32 v232, v1, v16
	v_add_u32_e32 v233, v1, v17
	v_add_u32_e32 v234, v1, v18
	v_add_u32_e32 v235, v1, v19
	v_add_u32_e32 v236, v1, v20
	v_add_u32_e32 v237, v1, v21
	v_add_u32_e32 v238, v199, v4
	v_add_u32_e32 v239, v199, v9
	v_add_u32_e32 v240, v199, v10
	v_add_u32_e32 v241, v199, v11
	v_add_u32_e32 v242, v199, v12
	v_add_u32_e32 v243, v199, v13
	v_and_b32_e32 v245, 0x1f8, v224
	v_lshlrev_b32_e32 v245, 1, v245
	v_add_u32_e32 v245, 0x10200, v245
	v_add_u32_e32 v238, v238, v245
	v_add_u32_e32 v245, 0x200, v245
	v_add_u32_e32 v239, v239, v245
	v_add_u32_e32 v245, 0x200, v245
	v_add_u32_e32 v240, v240, v245
	v_add_u32_e32 v245, 0x200, v245
	v_add_u32_e32 v241, v241, v245
	v_add_u32_e32 v245, 0x200, v245
	v_add_u32_e32 v242, v242, v245
	v_add_u32_e32 v245, 0x200, v245
	v_add_u32_e32 v243, v243, v245
	v_add_u32_e32 v244, 0, v8
	s_and_b32 s36, s95, 7
	s_lshl_b32 s36, s36, 3
	s_bfe_u32 s37, s95, 0x30003
	s_or_b32 s36, s36, s37
	s_and_b32 s37, s95, 0x40
	s_or_b32 s36, s36, s37
	s_branch .LBB0_299

; #define LAS __attribute__((address_space(3)))
; __device__ __forceinline__ unsigned pk2(float lo, float hi) { const f32x2_t v = {lo, hi}; const bf16x2_t b = __builtin_convertvector(v, bf16x2_t); return __builtin_bit_cast(unsigned, b); }
; __device__ __forceinline__ void ph_gla_scan(const Args& a, LAS unsigned char* lds) {
;     ...
;                 const int ccur = GS_CHUNK(n); const size_t row0 = (size_t)b * TB + (size_t)ccur * 64;
;                 bf16x8_t sa[8];
; #pragma unroll
;                 for (int p = 0; p < 8; ++p) { const v4u w = {pk2(s[2 * p][0], s[2 * p][1]), pk2(s[2 * p][2], s[2 * p][3]), pk2(s[2 * p + 1][0], s[2 * p + 1][1]), pk2(s[2 * p + 1][2], s[2 * p + 1][3])}; sa[p] = __builtin_bit_cast(bf16x8_t, w); }
;                 const LAS unsigned char* vrow = lds + L_V + (16 * wave + l16) * RS + kg * 16;
;                 const bf16x8_t vt0 = *(const LAS bf16x8_t*)(vrow), vt1 = *(const LAS bf16x8_t*)(vrow + 64);
;                 const LAS unsigned char* qrow = lds + l16 * QS + kg * 16; const LAS unsigned char* prow = lds + L_P + l16 * RS + kg * 16;
;                 f32x4 o4[4];
; #pragma unroll
;                 for (int tt = 0; tt < 4; ++tt) o4[tt] = (f32x4){0.f, 0.f, 0.f, 0.f};
; #pragma unroll
;                 for (int p = 0; p < 8; ++p) {
; #pragma unroll
;                     for (int tt = 0; tt < 4; ++tt) { const bf16x8_t qb = *(const LAS bf16x8_t*)(qrow + tt * 16 * QS + p * 64); o4[tt] = __builtin_amdgcn_mfma_f32_16x16x32_bf16(sa[p], qb, o4[tt], 0, 0, 0); } }
;                 if (dir == 0) {
; #pragma unroll
;                     for (int tt = 0; tt < 4; ++tt) { const bf16x8_t pb0 = *(const LAS bf16x8_t*)(prow + tt * 16 * RS); o4[tt] = __builtin_amdgcn_mfma_f32_16x16x32_bf16(vt0, pb0, o4[tt], 0, 0, 0); }
; #pragma unroll
;                     for (int tt = 0; tt < 4; ++tt) { const bf16x8_t pb1 = *(const LAS bf16x8_t*)(prow + tt * 16 * RS + 64); o4[tt] = __builtin_amdgcn_mfma_f32_16x16x32_bf16(vt1, pb1, o4[tt], 0, 0, 0); } }
; #pragma unroll
;                 for (int tt = 0; tt < 4; ++tt) *(v2u*)(O + (row0 + 16 * tt + l16) * 2048 + h * 512 + dvb * 64 + 16 * wave + 4 * kg) = (v2u){pk2(o4[tt][0], o4[tt][1]), pk2(o4[tt][2], o4[tt][3])};
;                 __syncthreads();
.LBB0_301:
	s_cmp_lt_u32 s19, 4
	s_cselect_b32 s2, 0x100, -4
	s_add_i32 s14, s2, s19
	s_and_b64 s[2:3], s[4:5], exec
	s_cselect_b32 s2, s14, s20
	s_ashr_i32 s3, s2, 31
	s_lshl_b64 s[2:3], s[2:3], 18
	v_cvt_pk_bf16_f32 v86, v86, v87
	v_cvt_pk_bf16_f32 v87, v88, v89
	v_lshl_add_u64 v[88:89], v[90:91], 0, s[2:3]
	v_cvt_pk_bf16_f32 v82, v82, v83
	v_cvt_pk_bf16_f32 v83, v84, v85
	v_add_co_u32_e32 v84, vcc, s30, v88
	v_cvt_pk_bf16_f32 v78, v78, v79
	s_nop 0
	v_addc_co_u32_e32 v85, vcc, 0, v89, vcc
	v_cvt_pk_bf16_f32 v79, v80, v81
	v_add_co_u32_e32 v80, vcc, s31, v88
	v_cvt_pk_bf16_f32 v74, v74, v75
	s_nop 0
	v_addc_co_u32_e32 v81, vcc, 0, v89, vcc
	v_cvt_pk_bf16_f32 v75, v76, v77
	v_add_co_u32_e32 v76, vcc, s33, v88
	global_store_dwordx2 v[88:89], v[86:87], off
	s_nop 0
	v_addc_co_u32_e32 v77, vcc, 0, v89, vcc
	global_store_dwordx2 v[84:85], v[82:83], off
	global_store_dwordx2 v[80:81], v[78:79], off
	global_store_dwordx2 v[76:77], v[74:75], off
	s_waitcnt lgkmcnt(0)
	s_barrier
; #define LAS __attribute__((address_space(3)))
; __device__ __forceinline__ void ph_gla_scan(const Args& a, LAS unsigned char* lds) {
;     ...
;                 const LAS unsigned char* krow = lds + L_K + l16 * RS + kg * 16; const LAS unsigned char* erow = lds + L_E + kg * 16;
; #pragma unroll
;                 for (int t = 0; t < 16; ++t) { const bf16x8_t ka0 = *(const LAS bf16x8_t*)(krow + t * 16 * RS); s[t] = __builtin_amdgcn_mfma_f32_16x16x32_bf16(ka0, vt0, s[t], 0, 0, 0); }
; #pragma unroll
;                 for (int t = 0; t < 16; ++t) { const bf16x8_t ka1 = *(const LAS bf16x8_t*)(krow + t * 16 * RS + 64); s[t] = __builtin_amdgcn_mfma_f32_16x16x32_bf16(ka1, vt1, s[t], 0, 0, 0); }
; #pragma unroll
;                 for (int t = 0; t < 16; ++t) { const f32x4 et = *(const LAS f32x4*)(erow + t * 64); s[t] = s[t] * et; }
	ds_read_b128 v[74:77], v144 offset:0
	ds_read_b128 v[78:81], v144 offset:64
	s_waitcnt lgkmcnt(1)
	v_mfma_f32_16x16x32_bf16 v[2:5], v[74:77], v[70:73], v[2:5]
	ds_read_b128 v[74:77], v144 offset:2560
	ds_read_b128 v[82:85], v144 offset:2624
	v_add_u32_e32 v1, 0, v181
	v_add_u32_e32 v1, 0x15c00, v1
	s_waitcnt lgkmcnt(1)
	v_mfma_f32_16x16x32_bf16 v[6:9], v[74:77], v[70:73], v[6:9]
	ds_read_b128 v[74:77], v144 offset:5120
	ds_read_b128 v[86:89], v144 offset:5184
	s_add_i32 s19, s19, 1
	s_add_i32 s20, s20, -1
	s_waitcnt lgkmcnt(1)
	v_mfma_f32_16x16x32_bf16 v[10:13], v[74:77], v[70:73], v[10:13]
	ds_read_b128 v[74:77], v144 offset:7680
	ds_read_b128 v[92:95], v144 offset:7744
	s_cmpk_lg_i32 s19, 0x104
	s_waitcnt lgkmcnt(1)
	v_mfma_f32_16x16x32_bf16 v[14:17], v[74:77], v[70:73], v[14:17]
	ds_read_b128 v[74:77], v144 offset:10240
	ds_read_b128 v[96:99], v144 offset:10304
	s_waitcnt lgkmcnt(1)
	v_mfma_f32_16x16x32_bf16 v[18:21], v[74:77], v[70:73], v[18:21]
	ds_read_b128 v[74:77], v144 offset:12800
	ds_read_b128 v[100:103], v144 offset:12864
	s_waitcnt lgkmcnt(1)
	v_mfma_f32_16x16x32_bf16 v[22:25], v[74:77], v[70:73], v[22:25]
	ds_read_b128 v[74:77], v144 offset:15360
	ds_read_b128 v[104:107], v144 offset:15424
	s_waitcnt lgkmcnt(1)
	v_mfma_f32_16x16x32_bf16 v[26:29], v[74:77], v[70:73], v[26:29]
	ds_read_b128 v[74:77], v144 offset:17920
	ds_read_b128 v[108:111], v144 offset:17984
	s_waitcnt lgkmcnt(1)
	v_mfma_f32_16x16x32_bf16 v[30:33], v[74:77], v[70:73], v[30:33]
	ds_read_b128 v[74:77], v144 offset:20480
	ds_read_b128 v[112:115], v144 offset:20544
	s_waitcnt lgkmcnt(1)
	v_mfma_f32_16x16x32_bf16 v[38:41], v[74:77], v[70:73], v[38:41]
	ds_read_b128 v[74:77], v144 offset:23040
	ds_read_b128 v[116:119], v144 offset:23104
	s_waitcnt lgkmcnt(1)
	v_mfma_f32_16x16x32_bf16 v[42:45], v[74:77], v[70:73], v[42:45]
	ds_read_b128 v[74:77], v144 offset:25600
	ds_read_b128 v[120:123], v144 offset:25664
	s_waitcnt lgkmcnt(1)
	v_mfma_f32_16x16x32_bf16 v[46:49], v[74:77], v[70:73], v[46:49]
	ds_read_b128 v[74:77], v144 offset:28160
	ds_read_b128 v[124:127], v144 offset:28224
	s_waitcnt lgkmcnt(1)
	v_mfma_f32_16x16x32_bf16 v[50:53], v[74:77], v[70:73], v[50:53]
	ds_read_b128 v[74:77], v144 offset:30720
	ds_read_b128 v[128:131], v144 offset:30784
	s_waitcnt lgkmcnt(1)
	v_mfma_f32_16x16x32_bf16 v[54:57], v[74:77], v[70:73], v[54:57]
	ds_read_b128 v[74:77], v144 offset:33280
	ds_read_b128 v[132:135], v144 offset:33344
	s_waitcnt lgkmcnt(1)
	v_mfma_f32_16x16x32_bf16 v[62:65], v[74:77], v[70:73], v[62:65]
	ds_read_b128 v[74:77], v144 offset:35840
	ds_read_b128 v[136:139], v144 offset:35904
	s_waitcnt lgkmcnt(1)
	v_mfma_f32_16x16x32_bf16 v[58:61], v[74:77], v[70:73], v[58:61]
	ds_read_b128 v[74:77], v144 offset:38400
	ds_read_b128 v[140:143], v144 offset:38464
	s_waitcnt lgkmcnt(1)
	v_mfma_f32_16x16x32_bf16 v[34:37], v[74:77], v[70:73], v[34:37]
	ds_read_b128 v[70:73], v1
	ds_read_b128 v[74:77], v1 offset:64
	v_mfma_f32_16x16x32_bf16 v[2:5], v[78:81], v[66:69], v[2:5]
	v_mfma_f32_16x16x32_bf16 v[6:9], v[82:85], v[66:69], v[6:9]
	v_mfma_f32_16x16x32_bf16 v[10:13], v[86:89], v[66:69], v[10:13]
	s_waitcnt lgkmcnt(1)
	s_nop 4
	v_pk_mul_f32 v[4:5], v[4:5], v[72:73]
	v_pk_mul_f32 v[2:3], v[2:3], v[70:71]
	ds_read_b128 v[70:73], v1 offset:128
	s_waitcnt lgkmcnt(1)
	v_pk_mul_f32 v[8:9], v[8:9], v[76:77]
	v_pk_mul_f32 v[6:7], v[6:7], v[74:75]
	ds_read_b128 v[74:77], v1 offset:192
	v_mfma_f32_16x16x32_bf16 v[14:17], v[92:95], v[66:69], v[14:17]
	s_waitcnt lgkmcnt(1)
	v_pk_mul_f32 v[12:13], v[12:13], v[72:73]
	v_pk_mul_f32 v[10:11], v[10:11], v[70:71]
	ds_read_b128 v[70:73], v1 offset:256
	v_mfma_f32_16x16x32_bf16 v[18:21], v[96:99], v[66:69], v[18:21]
	v_mfma_f32_16x16x32_bf16 v[22:25], v[100:103], v[66:69], v[22:25]
	s_waitcnt lgkmcnt(1)
	s_nop 0
	v_pk_mul_f32 v[16:17], v[16:17], v[76:77]
	v_pk_mul_f32 v[14:15], v[14:15], v[74:75]
	ds_read_b128 v[74:77], v1 offset:320
	s_waitcnt lgkmcnt(1)
	s_nop 0
	v_pk_mul_f32 v[20:21], v[20:21], v[72:73]
	v_pk_mul_f32 v[18:19], v[18:19], v[70:71]
	ds_read_b128 v[70:73], v1 offset:384
	v_mfma_f32_16x16x32_bf16 v[26:29], v[104:107], v[66:69], v[26:29]
	s_waitcnt lgkmcnt(1)
	v_pk_mul_f32 v[24:25], v[24:25], v[76:77]
	v_pk_mul_f32 v[22:23], v[22:23], v[74:75]
	ds_read_b128 v[74:77], v1 offset:448
	v_mfma_f32_16x16x32_bf16 v[30:33], v[108:111], v[66:69], v[30:33]
	v_mfma_f32_16x16x32_bf16 v[38:41], v[112:115], v[66:69], v[38:41]
	s_waitcnt lgkmcnt(1)
	s_nop 0
	v_pk_mul_f32 v[28:29], v[28:29], v[72:73]
	v_pk_mul_f32 v[26:27], v[26:27], v[70:71]
	ds_read_b128 v[70:73], v1 offset:512
	s_waitcnt lgkmcnt(1)
	s_nop 0
	v_pk_mul_f32 v[32:33], v[32:33], v[76:77]
	v_pk_mul_f32 v[30:31], v[30:31], v[74:75]
	ds_read_b128 v[74:77], v1 offset:576
	v_mfma_f32_16x16x32_bf16 v[42:45], v[116:119], v[66:69], v[42:45]
	s_waitcnt lgkmcnt(1)
	v_pk_mul_f32 v[40:41], v[40:41], v[72:73]
	v_pk_mul_f32 v[38:39], v[38:39], v[70:71]
	ds_read_b128 v[70:73], v1 offset:704
	v_mfma_f32_16x16x32_bf16 v[46:49], v[120:123], v[66:69], v[46:49]
	v_mfma_f32_16x16x32_bf16 v[50:53], v[124:127], v[66:69], v[50:53]
	s_waitcnt lgkmcnt(1)
	s_nop 0
	v_pk_mul_f32 v[44:45], v[44:45], v[76:77]
	v_pk_mul_f32 v[42:43], v[42:43], v[74:75]
	ds_read_b128 v[74:77], v1 offset:768
	v_mfma_f32_16x16x32_bf16 v[54:57], v[128:131], v[66:69], v[54:57]
	v_mfma_f32_16x16x32_bf16 v[62:65], v[132:135], v[66:69], v[62:65]
	s_waitcnt lgkmcnt(1)
	v_pk_mul_f32 v[52:53], v[52:53], v[72:73]
	v_pk_mul_f32 v[50:51], v[50:51], v[70:71]
	ds_read_b128 v[70:73], v1 offset:896
	v_mfma_f32_16x16x32_bf16 v[58:61], v[136:139], v[66:69], v[58:61]
	v_mfma_f32_16x16x32_bf16 v[34:37], v[140:143], v[66:69], v[34:37]
	ds_read_b128 v[66:69], v1 offset:640
	s_waitcnt lgkmcnt(0)
	v_pk_mul_f32 v[48:49], v[48:49], v[68:69]
	v_pk_mul_f32 v[46:47], v[46:47], v[66:67]
	ds_read_b128 v[66:69], v1 offset:832
	v_pk_mul_f32 v[56:57], v[56:57], v[76:77]
	v_pk_mul_f32 v[54:55], v[54:55], v[74:75]
	ds_read_b128 v[74:77], v1 offset:960
	v_pk_mul_f32 v[60:61], v[60:61], v[72:73]
	s_waitcnt lgkmcnt(1)
	v_pk_mul_f32 v[64:65], v[64:65], v[68:69]
	v_pk_mul_f32 v[62:63], v[62:63], v[66:67]
	v_pk_mul_f32 v[58:59], v[58:59], v[70:71]
	s_waitcnt lgkmcnt(0)
	v_pk_mul_f32 v[36:37], v[36:37], v[76:77]
	v_pk_mul_f32 v[34:35], v[34:35], v[74:75]
	s_cbranch_scc0 .LBB0_306

; #define GS_LOADK(S, n) do { const int c_ = GS_CHUNK(n); \
;             const bf16* kb_ = KDT + ((((size_t)(dir * 2 + b) * 4 + h) * 260 + c_) * 256) * 64; \
;             _Pragma("unroll") for (int j = 0; j < 8; ++j) S[j] = *(const v4u*)(kb_ + (size_t)(ht + 256 * j) * 8); \
;             if (ht < 64) S[8] = *(const v4u*)(ET + (((size_t)(dir * 2 + b) * 4 + h) * 260 + c_) * 256 + ht * 4); } while (0)
; #define GS_WRITEK(S) do { \
;             _Pragma("unroll") for (int j = 0; j < 8; ++j) { const int piece = ht + 256 * j; *(LAS v4u*)(lds + L_K + (piece >> 3) * RS + (piece & 7) * 16) = S[j]; } \
;             if (ht < 64) *(LAS v4u*)(lds + L_E + ht * 16) = S[8]; } while (0)
; __device__ __forceinline__ void ph_gla_scan(const Args& a, LAS unsigned char* lds) {
;     ...
; #pragma unroll
;             for (int j = 0; j < 12; ++j) { Qa[j] = (v4u){0u, 0u, 0u, 0u}; Qb[j] = (v4u){0u, 0u, 0u, 0u}; }
; #pragma unroll
;             for (int j = 0; j < 9; ++j) { Ka[j] = (v4u){0u, 0u, 0u, 0u}; Kb[j] = (v4u){0u, 0u, 0u, 0u}; }
;             GS_LOADQ(Qa, 0); GS_LOADK(Ka, 0); GS_LOADQ(Qb, 1); GS_LOADK(Kb, 1);
;             GS_WRITEQ(Qa); GS_LOADQ(Qa, 2);
;             __syncthreads();
;             for (int n = 0; n < 260; n += 2) {
;                 __syncthreads(); GS_WRITEK(Ka); if (n + 2 < 260) GS_LOADK(Ka, n + 2);
;                 __syncthreads(); GS_WRITEQ(Qb); if (n + 3 < 260) GS_LOADQ(Qb, n + 3);
;                 __syncthreads(); GS_WRITEK(Kb); if (n + 3 < 260) GS_LOADK(Kb, n + 3);
;                 __syncthreads(); if (n + 2 < 260) { GS_WRITEQ(Qa); } if (n + 4 < 260) GS_LOADQ(Qa, n + 4);
;             }
.LBB0_322:
	v_add_u32_e32 v221, v199, v225
	v_and_b32_e32 v245, 0x1f8, v224
	v_lshlrev_b32_e32 v245, 1, v245
	v_add_u32_e32 v245, 0xfe00, v245
	v_add_u32_e32 v221, v221, v245
	v_add3_u32 v245, v199, v226, v245
	v_add_u32_e32 v245, 0x200, v245
	v_add_u32_e32 v246, 0x15c00, v244
	s_waitcnt lgkmcnt(0)
	s_barrier
	s_barrier
	ds_write_b128 v221, v[32:35] offset:32768
	ds_write_b128 v245, v[28:31] offset:32768
	ds_write_b128 v238, v[36:39] offset:32768
	ds_write_b128 v239, v[40:43] offset:32768
	ds_write_b128 v240, v[44:47] offset:32768
	ds_write_b128 v241, v[48:51] offset:32768
	ds_write_b128 v242, v[52:55] offset:32768
	ds_write_b128 v243, v[56:59] offset:32768
	s_and_saveexec_b64 s[14:15], s[0:1]
	ds_write_b128 v246, v[12:15]
	s_or_b64 exec, exec, s[14:15]
	s_add_u32 s14, s42, s3
	s_addc_u32 s15, s41, 0
	s_lshl_b64 s[16:17], s[14:15], 15
	s_add_u32 s16, s22, s16
	s_addc_u32 s17, s23, s17
	v_lshl_add_u64 v[28:29], s[16:17], 0, v[204:205]
	v_lshl_add_u64 v[32:33], s[16:17], 0, v[186:187]
	v_lshl_add_u64 v[36:37], s[16:17], 0, v[206:207]
	v_lshl_add_u64 v[40:41], s[16:17], 0, v[208:209]
	v_lshl_add_u64 v[44:45], s[16:17], 0, v[210:211]
	v_lshl_add_u64 v[48:49], s[16:17], 0, v[212:213]
	v_lshl_add_u64 v[52:53], s[16:17], 0, v[214:215]
	v_lshl_add_u64 v[56:57], s[16:17], 0, v[216:217]
	global_load_dwordx4 v[28:31], v[28:29], off
	s_nop 0
	global_load_dwordx4 v[32:35], v[32:33], off
	s_nop 0
	global_load_dwordx4 v[36:39], v[36:37], off
	s_nop 0
	global_load_dwordx4 v[40:43], v[40:41], off
	s_nop 0
	global_load_dwordx4 v[44:47], v[44:45], off
	s_nop 0
	global_load_dwordx4 v[48:51], v[48:49], off
	s_nop 0
	global_load_dwordx4 v[52:55], v[52:53], off
	s_nop 0
	global_load_dwordx4 v[56:59], v[56:57], off
	s_and_saveexec_b64 s[16:17], s[0:1]
	s_cbranch_execz .LBB0_326
	s_lshl_b64 s[14:15], s[14:15], 10
	v_lshl_add_u64 v[12:13], v[184:185], 0, s[14:15]
	global_load_dwordx4 v[12:15], v[12:13], off

; #define GS_LOADK(S, n) do { const int c_ = GS_CHUNK(n); \
;             const bf16* kb_ = KDT + ((((size_t)(dir * 2 + b) * 4 + h) * 260 + c_) * 256) * 64; \
;             _Pragma("unroll") for (int j = 0; j < 8; ++j) S[j] = *(const v4u*)(kb_ + (size_t)(ht + 256 * j) * 8); \
;             if (ht < 64) S[8] = *(const v4u*)(ET + (((size_t)(dir * 2 + b) * 4 + h) * 260 + c_) * 256 + ht * 4); } while (0)
; #define GS_WRITEK(S) do { \
;             _Pragma("unroll") for (int j = 0; j < 8; ++j) { const int piece = ht + 256 * j; *(LAS v4u*)(lds + L_K + (piece >> 3) * RS + (piece & 7) * 16) = S[j]; } \
;             if (ht < 64) *(LAS v4u*)(lds + L_E + ht * 16) = S[8]; } while (0)
; __device__ __forceinline__ void ph_gla_scan(const Args& a, LAS unsigned char* lds) {
;     ...
; #pragma unroll
;             for (int j = 0; j < 12; ++j) { Qa[j] = (v4u){0u, 0u, 0u, 0u}; Qb[j] = (v4u){0u, 0u, 0u, 0u}; }
; #pragma unroll
;             for (int j = 0; j < 9; ++j) { Ka[j] = (v4u){0u, 0u, 0u, 0u}; Kb[j] = (v4u){0u, 0u, 0u, 0u}; }
;             GS_LOADQ(Qa, 0); GS_LOADK(Ka, 0); GS_LOADQ(Qb, 1); GS_LOADK(Kb, 1);
;             GS_WRITEQ(Qa); GS_LOADQ(Qa, 2);
;             __syncthreads();
;             for (int n = 0; n < 260; n += 2) {
;                 __syncthreads(); GS_WRITEK(Ka); if (n + 2 < 260) GS_LOADK(Ka, n + 2);
;                 __syncthreads(); GS_WRITEQ(Qb); if (n + 3 < 260) GS_LOADQ(Qb, n + 3);
;                 __syncthreads(); GS_WRITEK(Kb); if (n + 3 < 260) GS_LOADK(Kb, n + 3);
;                 __syncthreads(); if (n + 2 < 260) { GS_WRITEQ(Qa); } if (n + 4 < 260) GS_LOADQ(Qa, n + 4);
;             }
.LBB0_330:
	s_waitcnt lgkmcnt(0)
	s_barrier
	ds_write_b128 v221, v[92:95] offset:32768
	ds_write_b128 v245, v[96:99] offset:32768
	ds_write_b128 v238, v[100:103] offset:32768
	ds_write_b128 v239, v[104:107] offset:32768
	ds_write_b128 v240, v[116:119] offset:32768
	ds_write_b128 v241, v[120:123] offset:32768
	ds_write_b128 v242, v[124:127] offset:32768
	ds_write_b128 v243, v[128:131] offset:32768
	s_and_saveexec_b64 s[14:15], s[0:1]
	ds_write_b128 v246, v[24:27]
	s_or_b64 exec, exec, s[14:15]
	s_and_b64 s[2:3], s[12:13], exec
	s_cselect_b32 s2, s34, 0x100
	s_add_u32 s14, s42, s2
	s_addc_u32 s15, s41, 0
	s_lshl_b64 s[2:3], s[14:15], 15
	s_add_u32 s2, s22, s2
	s_addc_u32 s3, s23, s3
	v_lshl_add_u64 v[92:93], s[2:3], 0, v[204:205]
	v_lshl_add_u64 v[96:97], s[2:3], 0, v[186:187]
	v_lshl_add_u64 v[100:101], s[2:3], 0, v[206:207]
	v_lshl_add_u64 v[104:105], s[2:3], 0, v[208:209]
	v_lshl_add_u64 v[116:117], s[2:3], 0, v[210:211]
	v_lshl_add_u64 v[120:121], s[2:3], 0, v[212:213]
	v_lshl_add_u64 v[124:125], s[2:3], 0, v[214:215]
	v_lshl_add_u64 v[128:129], s[2:3], 0, v[216:217]
	global_load_dwordx4 v[92:95], v[92:93], off
	s_nop 0
	global_load_dwordx4 v[96:99], v[96:97], off
	s_nop 0
	global_load_dwordx4 v[100:103], v[100:101], off
	s_nop 0
	global_load_dwordx4 v[104:107], v[104:105], off
	s_nop 0
	global_load_dwordx4 v[116:119], v[116:117], off
	s_nop 0
	global_load_dwordx4 v[120:123], v[120:121], off
	s_nop 0
	global_load_dwordx4 v[124:127], v[124:125], off
	s_nop 0
	global_load_dwordx4 v[128:131], v[128:129], off
	s_and_saveexec_b64 s[16:17], s[0:1]
	s_cbranch_execz .LBB0_334
	s_lshl_b64 s[2:3], s[14:15], 10
	v_lshl_add_u64 v[24:25], v[184:185], 0, s[2:3]
	global_load_dwordx4 v[24:27], v[24:25], off

; #define GS_LOADK(S, n) do { const int c_ = GS_CHUNK(n); \
;             const bf16* kb_ = KDT + ((((size_t)(dir * 2 + b) * 4 + h) * 260 + c_) * 256) * 64; \
;             _Pragma("unroll") for (int j = 0; j < 8; ++j) S[j] = *(const v4u*)(kb_ + (size_t)(ht + 256 * j) * 8); \
;             if (ht < 64) S[8] = *(const v4u*)(ET + (((size_t)(dir * 2 + b) * 4 + h) * 260 + c_) * 256 + ht * 4); } while (0)
; #define GS_WRITEK(S) do { \
;             _Pragma("unroll") for (int j = 0; j < 8; ++j) { const int piece = ht + 256 * j; *(LAS v4u*)(lds + L_K + (piece >> 3) * RS + (piece & 7) * 16) = S[j]; } \
;             if (ht < 64) *(LAS v4u*)(lds + L_E + ht * 16) = S[8]; } while (0)
; __device__ __forceinline__ void ph_gla_scan(const Args& a, LAS unsigned char* lds) {
;     ...
; #pragma unroll
;             for (int j = 0; j < 12; ++j) { Qa[j] = (v4u){0u, 0u, 0u, 0u}; Qb[j] = (v4u){0u, 0u, 0u, 0u}; }
; #pragma unroll
;             for (int j = 0; j < 9; ++j) { Ka[j] = (v4u){0u, 0u, 0u, 0u}; Kb[j] = (v4u){0u, 0u, 0u, 0u}; }
;             GS_LOADQ(Qa, 0); GS_LOADK(Ka, 0); GS_LOADQ(Qb, 1); GS_LOADK(Kb, 1);
;             GS_WRITEQ(Qa); GS_LOADQ(Qa, 2);
;             __syncthreads();
;             for (int n = 0; n < 260; n += 2) {
;                 __syncthreads(); GS_WRITEK(Ka); if (n + 2 < 260) GS_LOADK(Ka, n + 2);
;                 __syncthreads(); GS_WRITEQ(Qb); if (n + 3 < 260) GS_LOADQ(Qb, n + 3);
;                 __syncthreads(); GS_WRITEK(Kb); if (n + 3 < 260) GS_LOADK(Kb, n + 3);
;                 __syncthreads(); if (n + 2 < 260) { GS_WRITEQ(Qa); } if (n + 4 < 260) GS_LOADQ(Qa, n + 4);
;             }
.LBB0_340:
	s_waitcnt lgkmcnt(0)
	s_barrier
	s_waitcnt vmcnt(7)
	ds_write_b128 v221, v[28:31] offset:32768
	s_waitcnt vmcnt(6)
	ds_write_b128 v245, v[32:35] offset:32768
	s_waitcnt vmcnt(5)
	ds_write_b128 v238, v[36:39] offset:32768
	s_waitcnt vmcnt(4)
	ds_write_b128 v239, v[40:43] offset:32768
	s_waitcnt vmcnt(3)
	ds_write_b128 v240, v[44:47] offset:32768
	s_waitcnt vmcnt(2)
	ds_write_b128 v241, v[48:51] offset:32768
	s_waitcnt vmcnt(1)
	ds_write_b128 v242, v[52:55] offset:32768
	s_waitcnt vmcnt(0)
	ds_write_b128 v243, v[56:59] offset:32768
	s_and_saveexec_b64 s[14:15], s[0:1]
	ds_write_b128 v246, v[12:15]
	s_or_b64 exec, exec, s[14:15]
	s_cmpk_lt_u32 s2, 0x102
	s_cselect_b64 s[16:17], -1, 0
	s_cmpk_gt_u32 s2, 0x101
	s_cselect_b64 s[14:15], -1, 0
	s_and_b64 vcc, exec, s[14:15]
	s_cbranch_vccnz .LBB0_346
	s_add_i32 s10, s3, 2
	s_add_i32 s20, s2, -2
	s_and_b64 s[18:19], s[12:13], exec
	s_cselect_b32 s10, s20, s10
	s_add_u32 s18, s42, s10
	s_addc_u32 s19, s41, 0
	s_lshl_b64 s[20:21], s[18:19], 15
	s_add_u32 s20, s22, s20
	s_addc_u32 s21, s23, s21
	v_lshl_add_u64 v[28:29], s[20:21], 0, v[204:205]
	v_lshl_add_u64 v[32:33], s[20:21], 0, v[186:187]
	v_lshl_add_u64 v[36:37], s[20:21], 0, v[206:207]
	v_lshl_add_u64 v[40:41], s[20:21], 0, v[208:209]
	v_lshl_add_u64 v[44:45], s[20:21], 0, v[210:211]
	v_lshl_add_u64 v[48:49], s[20:21], 0, v[212:213]
	v_lshl_add_u64 v[52:53], s[20:21], 0, v[214:215]
	v_lshl_add_u64 v[56:57], s[20:21], 0, v[216:217]
	global_load_dwordx4 v[28:31], v[28:29], off
	s_nop 0
	global_load_dwordx4 v[32:35], v[32:33], off
	s_nop 0
	global_load_dwordx4 v[36:39], v[36:37], off
	s_nop 0
	global_load_dwordx4 v[40:43], v[40:41], off
	s_nop 0
	global_load_dwordx4 v[44:47], v[44:45], off
	s_nop 0
	global_load_dwordx4 v[48:51], v[48:49], off
	s_nop 0
	global_load_dwordx4 v[52:55], v[52:53], off
	s_nop 0
	global_load_dwordx4 v[56:59], v[56:57], off
	s_and_saveexec_b64 s[20:21], s[0:1]
	s_cbranch_execz .LBB0_345
	s_lshl_b64 s[18:19], s[18:19], 10
	v_lshl_add_u64 v[12:13], v[184:185], 0, s[18:19]
	global_load_dwordx4 v[12:15], v[12:13], off

; #define GS_LOADK(S, n) do { const int c_ = GS_CHUNK(n); \
;             const bf16* kb_ = KDT + ((((size_t)(dir * 2 + b) * 4 + h) * 260 + c_) * 256) * 64; \
;             _Pragma("unroll") for (int j = 0; j < 8; ++j) S[j] = *(const v4u*)(kb_ + (size_t)(ht + 256 * j) * 8); \
;             if (ht < 64) S[8] = *(const v4u*)(ET + (((size_t)(dir * 2 + b) * 4 + h) * 260 + c_) * 256 + ht * 4); } while (0)
; #define GS_WRITEK(S) do { \
;             _Pragma("unroll") for (int j = 0; j < 8; ++j) { const int piece = ht + 256 * j; *(LAS v4u*)(lds + L_K + (piece >> 3) * RS + (piece & 7) * 16) = S[j]; } \
;             if (ht < 64) *(LAS v4u*)(lds + L_E + ht * 16) = S[8]; } while (0)
; __device__ __forceinline__ void ph_gla_scan(const Args& a, LAS unsigned char* lds) {
;     ...
; #pragma unroll
;             for (int j = 0; j < 12; ++j) { Qa[j] = (v4u){0u, 0u, 0u, 0u}; Qb[j] = (v4u){0u, 0u, 0u, 0u}; }
; #pragma unroll
;             for (int j = 0; j < 9; ++j) { Ka[j] = (v4u){0u, 0u, 0u, 0u}; Kb[j] = (v4u){0u, 0u, 0u, 0u}; }
;             GS_LOADQ(Qa, 0); GS_LOADK(Ka, 0); GS_LOADQ(Qb, 1); GS_LOADK(Kb, 1);
;             GS_WRITEQ(Qa); GS_LOADQ(Qa, 2);
;             __syncthreads();
;             for (int n = 0; n < 260; n += 2) {
;                 __syncthreads(); GS_WRITEK(Ka); if (n + 2 < 260) GS_LOADK(Ka, n + 2);
;                 __syncthreads(); GS_WRITEQ(Qb); if (n + 3 < 260) GS_LOADQ(Qb, n + 3);
;                 __syncthreads(); GS_WRITEK(Kb); if (n + 3 < 260) GS_LOADK(Kb, n + 3);
;                 __syncthreads(); if (n + 2 < 260) { GS_WRITEQ(Qa); } if (n + 4 < 260) GS_LOADQ(Qa, n + 4);
;             }
.LBB0_351:
	s_waitcnt lgkmcnt(0)
	s_barrier
	s_waitcnt vmcnt(17)
	ds_write_b128 v221, v[92:95] offset:32768
	s_waitcnt vmcnt(16)
	ds_write_b128 v245, v[96:99] offset:32768
	s_waitcnt vmcnt(15)
	ds_write_b128 v238, v[100:103] offset:32768
	s_waitcnt vmcnt(14)
	ds_write_b128 v239, v[104:107] offset:32768
	s_waitcnt vmcnt(13)
	ds_write_b128 v240, v[116:119] offset:32768
	s_waitcnt vmcnt(12)
	ds_write_b128 v241, v[120:123] offset:32768
	s_waitcnt vmcnt(11)
	ds_write_b128 v242, v[124:127] offset:32768
	s_waitcnt vmcnt(10)
	ds_write_b128 v243, v[128:131] offset:32768
	s_and_saveexec_b64 s[20:21], s[0:1]
	ds_write_b128 v246, v[24:27]
	s_or_b64 exec, exec, s[20:21]
	s_andn2_b64 vcc, exec, s[18:19]
	s_cbranch_vccnz .LBB0_357
	s_add_i32 s10, s3, 1
	s_add_i32 s20, s2, -1
	s_and_b64 s[18:19], s[12:13], exec
	s_cselect_b32 s10, s20, s10
	s_add_u32 s18, s42, s10
	s_addc_u32 s19, s41, 0
	s_lshl_b64 s[20:21], s[18:19], 15
	s_add_u32 s20, s22, s20
	s_addc_u32 s21, s23, s21
	v_lshl_add_u64 v[92:93], s[20:21], 0, v[204:205]
	v_lshl_add_u64 v[96:97], s[20:21], 0, v[186:187]
	v_lshl_add_u64 v[100:101], s[20:21], 0, v[206:207]
	v_lshl_add_u64 v[104:105], s[20:21], 0, v[208:209]
	v_lshl_add_u64 v[116:117], s[20:21], 0, v[210:211]
	v_lshl_add_u64 v[120:121], s[20:21], 0, v[212:213]
	v_lshl_add_u64 v[124:125], s[20:21], 0, v[214:215]
	v_lshl_add_u64 v[128:129], s[20:21], 0, v[216:217]
	global_load_dwordx4 v[92:95], v[92:93], off
	s_nop 0
	global_load_dwordx4 v[96:99], v[96:97], off
	s_nop 0
	global_load_dwordx4 v[100:103], v[100:101], off
	s_nop 0
	global_load_dwordx4 v[104:107], v[104:105], off
	s_nop 0
	global_load_dwordx4 v[116:119], v[116:117], off
	s_nop 0
	global_load_dwordx4 v[120:123], v[120:121], off
	s_nop 0
	global_load_dwordx4 v[124:127], v[124:125], off
	s_nop 0
	global_load_dwordx4 v[128:131], v[128:129], off
	s_and_saveexec_b64 s[20:21], s[0:1]
	s_cbranch_execz .LBB0_356
	s_lshl_b64 s[18:19], s[18:19], 10
	v_lshl_add_u64 v[24:25], v[184:185], 0, s[18:19]
	global_load_dwordx4 v[24:27], v[24:25], off
